# v36 + counted vmcnt(20) at the HGRN pass-A chunk-loop top (no wait on the previous chunk's stores) + mini-GEMM fragment reads issued before the LDS-DMA stage loads
# baseline (speedup 1.0000x reference)
; __device__ __forceinline__ float fexp(float x) { return __builtin_amdgcn_exp2f(x * 1.4426950408889634f); }
; __device__ __forceinline__ void hgrn_a(unsigned char* lds, const Params& p, int jl, bf16_t* proj, bf16_t* mix, float* dbuf, bf16_t* scr, float* useg, float* dseg, int blk, int G, int tid) {
;     ...
;         const int nvalid = samp ? 32 : 64;
;         const int ch = h * 128 + c;
;         float lb = 0.f;
;         if (jl == 1) { const float a0 = p.lb[ch], a1 = p.lb[2048 + ch]; lb = 1.f / (1.f + fexp(a0 - a1)); }
;         const float lbe = fmaxf(lb, 1e-30f), oml = 1.f - lb;
;         f32x4 U[8];
; #pragma unroll
;         for (int kti = 0; kti < 8; ++kti) U[kti] = (f32x4){0.f, 0.f, 0.f, 0.f};
;         float bsum = 0.f;
;         const int lrow = tid >> 4, lcc = tid & 15, vkey = tid & 63, vdc = tid >> 6;
;         bf16x8 rq0, rq1, rz0, rz1, rv0, rv1;
;         const bf16x8 zero8 = {0, 0, 0, 0, 0, 0, 0, 0};
;     ...
;         HA_LOAD(0);
.LBB0_241:
	s_or_b64 exec, exec, s[6:7]
	s_mov_b32 s4, s36
	s_add_u32 s2, s84, s28
	v_writelane_b32 v255, s4, 49
	s_addc_u32 s3, s85, 0
	s_add_i32 s16, s9, 0x200
	v_writelane_b32 v255, s5, 50
	s_add_i32 s4, s36, 0xffffff00
	s_mul_hi_u32 s5, s4, 0xc000
	s_mul_i32 s4, s4, 0xc000
	v_readlane_b32 s6, v253, 35
	s_add_u32 s36, s6, s4
	v_readlane_b32 s4, v253, 36
	s_addc_u32 s37, s4, s5
	s_add_u32 s72, s36, 0x4000
	s_addc_u32 s73, s37, 0
	s_add_u32 s68, s36, 0x8000
	v_cmp_gt_i32_e32 vcc, s8, v90
	s_addc_u32 s69, s37, 0
	s_or_b64 s[76:77], s[22:23], vcc
	v_cmp_gt_i32_e32 vcc, s8, v94
	s_or_b64 s[78:79], s[22:23], vcc
	v_cmp_gt_i32_e32 vcc, s8, v96
	s_or_b64 s[80:81], s[22:23], vcc
	v_cmp_gt_i32_e32 vcc, s8, v98
	s_or_b64 s[82:83], s[22:23], vcc
	v_cmp_gt_i32_e32 vcc, s8, v100
	s_or_b64 s[84:85], s[22:23], vcc
	v_cmp_gt_i32_e32 vcc, s8, v102
	s_or_b64 s[86:87], s[22:23], vcc
	v_cmp_gt_i32_e32 vcc, s8, v104
	s_or_b64 s[88:89], s[22:23], vcc
	v_cmp_gt_i32_e32 vcc, s8, v106
	s_or_b64 s[90:91], s[22:23], vcc
	v_cmp_gt_i32_e32 vcc, s8, v108
	s_or_b64 s[92:93], s[22:23], vcc
	v_cmp_gt_i32_e32 vcc, s8, v110
	s_or_b64 s[94:95], s[22:23], vcc
	v_cmp_gt_i32_e32 vcc, s8, v112
	s_or_b64 s[96:97], s[22:23], vcc
	v_cmp_gt_i32_e32 vcc, s8, v114
	v_readlane_b32 s4, v253, 33
	s_or_b64 s[98:99], s[22:23], vcc
	v_cmp_gt_i32_e32 vcc, s8, v116
	v_max_f32_e32 v20, v19, v19
	v_sub_f32_e32 v169, 1.0, v19
	v_mov_b32_e32 v19, v1
	v_readlane_b32 s5, v253, 34
	s_or_b64 s[12:13], s[22:23], vcc
	v_cmp_gt_i32_e32 vcc, s8, v118
	v_lshl_add_u64 v[138:139], s[4:5], 0, v[18:19]
	s_or_b64 s[4:5], s[22:23], vcc
	v_cmp_gt_i32_e32 vcc, s8, v120
	v_mov_b32_e32 v54, v1
	v_mov_b32_e32 v55, v1
	v_max_f32_e32 v168, 0xda24260, v20
	s_or_b64 s[6:7], s[22:23], vcc
	v_cmp_gt_i32_e32 vcc, s8, v122
	v_mov_b32_e32 v56, v1
	v_mov_b32_e32 v57, v1
	v_mov_b64_e32 v[42:43], v[54:55]
	s_waitcnt lgkmcnt(0)
	v_mov_b64_e32 v[34:35], v[54:55]
	v_mov_b64_e32 v[30:31], v[54:55]
	v_mov_b64_e32 v[50:51], v[54:55]
	v_mov_b64_e32 v[26:27], v[54:55]
	v_mov_b64_e32 v[22:23], v[54:55]
	v_mov_b64_e32 v[18:19], v[54:55]
	v_cmp_gt_u32_e64 s[74:75], s8, v101
	v_lshl_add_u64 v[140:141], v[92:93], 0, s[28:29]
	s_or_b64 s[8:9], s[22:23], vcc
	s_mov_b32 s17, 0
	v_mov_b64_e32 v[44:45], v[56:57]
	v_mov_b64_e32 v[36:37], v[56:57]
	v_mov_b64_e32 v[32:33], v[56:57]
	v_mov_b64_e32 v[52:53], v[56:57]
	v_mov_b64_e32 v[28:29], v[56:57]
	v_mov_b64_e32 v[24:25], v[56:57]
	v_mov_b64_e32 v[20:21], v[56:57]
	s_waitcnt vmcnt(0)
	s_branch .LBB0_243

; __device__ __forceinline__ void hgrn_a(unsigned char* lds, const Params& p, int jl, bf16_t* proj, bf16_t* mix, float* dbuf, bf16_t* scr, float* useg, float* dseg, int blk, int G, int tid) {
;     ...
;         for (int n = 0; n < nch; ++n) {
;             int row0, didx, dstride; bf16_t *qd, *kd, *vd;
;             if (!samp) { row0 = (chunk0 + n) * 64; didx = chunk0 + n; bf16_t* base = proj + (size_t)row0 * N4 + h * 128; qd = base; kd = base + 2048; vd = base + 4096; dstride = N4; }
;             else { row0 = MPR + b * 32; didx = 512 + b; bf16_t* base = scr + (size_t)(u - 256) * 3 * 8192; qd = base; kd = base + 8192; vd = base + 16384; dstride = 128; }
;             *(bf16x8*)(RAWQ + lrow * 136 + lcc * 8) = rq0; *(bf16x8*)(RAWQ + (lrow + 32) * 136 + lcc * 8) = rq1;
;             *(bf16x8*)(RAWZ + lrow * 136 + lcc * 8) = rz0; *(bf16x8*)(RAWZ + (lrow + 32) * 136 + lcc * 8) = rz1;
; #pragma unroll
;             for (int e = 0; e < 8; ++e) { VTL[(vdc * 8 + e) * 72 + vkey] = (bf16_t)rv0[e]; VTL[((vdc + 8) * 8 + e) * 72 + vkey] = (bf16_t)rv1[e]; }
;             if (n + 1 < nch) HA_LOAD(n + 1);
.LBB0_245:
	s_add_i32 s17, s17, 1
	s_cmp_ge_u32 s17, s42
	s_waitcnt vmcnt(20)
	ds_write_b128 v77, v[6:9]
	ds_write_b128 v83, v[14:17]
	s_waitcnt vmcnt(20)
	ds_write_b128 v77, v[10:13] offset:17408
	ds_write_b128 v83, v[2:5] offset:17408
	ds_write_b16 v159, v38
	ds_write_b16 v159, v46 offset:9216
	ds_write_b16_d16_hi v159, v38 offset:144
	ds_write_b16_d16_hi v159, v46 offset:9360
	ds_write_b16 v159, v39 offset:288
	ds_write_b16 v159, v47 offset:9504
	ds_write_b16_d16_hi v159, v39 offset:432
	ds_write_b16_d16_hi v159, v47 offset:9648
	ds_write_b16 v159, v40 offset:576
	ds_write_b16 v159, v48 offset:9792
	ds_write_b16_d16_hi v159, v40 offset:720
	ds_write_b16_d16_hi v159, v48 offset:9936
	ds_write_b16 v159, v41 offset:864
	ds_write_b16 v159, v49 offset:10080
	ds_write_b16_d16_hi v159, v41 offset:1008
	ds_write_b16_d16_hi v159, v49 offset:10224
	s_cbranch_scc1 .LBB0_253
	s_add_i32 s28, s14, 64
	s_and_b64 s[38:39], s[22:23], exec
	s_cselect_b32 s38, s28, s43
	s_ashr_i32 s39, s38, 31
	s_lshl_b64 s[38:39], s[38:39], 14
	v_mov_b32_e32 v4, v1
	v_mov_b32_e32 v5, v1
	s_add_u32 s38, s2, s38
	v_mov_b32_e32 v2, 0
	v_mov_b32_e32 v3, v1
	v_mov_b64_e32 v[12:13], v[4:5]
	v_mov_b64_e32 v[8:9], v[4:5]
	s_addc_u32 s39, s3, s39
	v_mov_b64_e32 v[10:11], v[2:3]
	v_mov_b64_e32 v[6:7], v[2:3]
	s_mov_b64 s[40:41], exec
	v_readlane_b32 vcc_lo, v255, 43
	v_readlane_b32 vcc_hi, v255, 44
	s_and_b64 vcc, s[40:41], vcc
	s_mov_b64 exec, vcc
	s_cbranch_execz .LBB0_248
	v_lshl_add_u64 v[6:7], s[38:39], 0, v[78:79]
	v_mov_b32_e32 v135, v1
	v_lshl_add_u64 v[6:7], v[6:7], 0, v[134:135]
	v_add_co_u32_e32 v10, vcc, 0x1000, v6
	s_nop 1
	v_addc_co_u32_e32 v11, vcc, 0, v7, vcc
	global_load_dwordx4 v[6:9], v[6:7], off
	s_nop 0
	global_load_dwordx4 v[10:13], v[10:11], off
